# kernel start: relative-position-bias tables staged into LDS by LDS-DMA without waiting (was three serialized load/wait/ds_write rounds before the first barrier)
# baseline (speedup 1.0000x reference)
.LBB0_6:
	s_or_b64 exec, exec, s[22:23]
	v_readfirstlane_b32 s4, v4
	v_readfirstlane_b32 s5, v5
	v_lshlrev_b32_e32 v6, 2, v1
	s_lshr_b32 s3, s93, 6
	s_lshl_b32 s3, s3, 8
	s_add_i32 s3, s3, 0x22100
	s_nop 3
	s_mov_b32 m0, s3
	s_nop 0
	global_load_lds_dword v6, s[4:5]
	s_add_u32 s4, s4, 0x800
	s_addc_u32 s5, s5, 0
	s_add_i32 m0, s3, 0x800
	s_nop 0
	global_load_lds_dword v6, s[4:5]
	s_add_u32 s4, s4, 0x800
	s_addc_u32 s5, s5, 0
	s_add_i32 m0, s3, 0x1000
	s_nop 0
	global_load_lds_dword v6, s[4:5]
	s_add_u32 s4, s4, 0x800
	s_addc_u32 s5, s5, 0
	s_add_i32 m0, s3, 0x1800
	s_nop 0
	global_load_lds_dword v6, s[4:5]
	s_add_u32 s4, s4, 0x800
	s_addc_u32 s5, s5, 0
	s_add_i32 m0, s3, 0x2000
	s_nop 0
	global_load_lds_dword v6, s[4:5]
	s_add_u32 s4, s4, 0x800
	s_addc_u32 s5, s5, 0
	s_add_i32 m0, s3, 0x2800
	s_nop 0
	global_load_lds_dword v6, s[4:5]
	s_add_u32 s4, s4, 0x800
	s_addc_u32 s5, s5, 0
	s_add_i32 m0, s3, 0x3000
	s_nop 0
	global_load_lds_dword v6, s[4:5]
	s_add_u32 s4, s4, 0x800
	s_addc_u32 s5, s5, 0
	s_movk_i32 s6, 0x88
	v_cmp_gt_u32_e32 vcc, s6, v1
	s_and_saveexec_b64 s[6:7], vcc
	s_cbranch_execz .Lrpb_done
	s_add_i32 m0, s3, 0x3800
	s_nop 0
	global_load_lds_dword v6, s[4:5]
.Lrpb_done:
	s_or_b64 exec, exec, s[6:7]
	v_cmp_gt_u32_e32 vcc, 8, v1
	s_and_saveexec_b64 s[4:5], vcc
	v_lshl_add_u32 v2, v1, 2, 0
	v_add_u32_e32 v2, 0x20000, v2
	v_mov_b32_e32 v3, 0
	ds_write_b32 v2, v3
	s_or_b64 exec, exec, s[4:5]
	s_waitcnt lgkmcnt(0)
	s_waitcnt lgkmcnt(0)
	s_barrier
	s_load_dwordx2 s[40:41], s[0:1], 0x118
	s_add_u32 s0, s54, 0xd600000
	s_addc_u32 s1, s55, 0
	v_writelane_b32 v246, s0, 3
	s_nop 1
	v_writelane_b32 v246, s1, 4
	s_waitcnt lgkmcnt(0)
	s_sub_i32 s0, s41, s40
	s_cmp_lt_i32 s0, 2
	s_mov_b32 s0, 0
	v_writelane_b32 v246, s0, 5
	s_cbranch_scc1 .LBB0_17
	s_getreg_b32 s0, hwreg(HW_REG_XCC_ID, 0, 4)
	s_and_b32 s0, s0, 15
	v_writelane_b32 v246, s0, 5
	s_mov_b64 s[0:1], exec
	v_readlane_b32 s4, v246, 0
	v_readlane_b32 s5, v246, 1
	s_and_b64 s[4:5], s[0:1], s[4:5]
	s_mov_b64 exec, s[4:5]
	s_cbranch_execz .LBB0_16
	s_mov_b64 s[4:5], exec
	v_mbcnt_lo_u32_b32 v2, s4, 0
	v_mbcnt_hi_u32_b32 v2, s5, v2
	v_cmp_eq_u32_e32 vcc, 0, v2
	s_and_b64 s[6:7], exec, vcc
	s_mov_b64 exec, s[6:7]
	s_cbranch_execz .LBB0_16
	v_readlane_b32 s3, v246, 5
	s_bcnt1_i32_b64 s4, s[4:5]
	s_lshl_b32 s3, s3, 8
	v_mov_b32_e32 v3, s4
	v_readlane_b32 s4, v246, 3
	v_mov_b32_e32 v2, s3
	v_readlane_b32 s5, v246, 4
	s_nop 4
	global_atomic_add v2, v3, s[4:5] offset:1024
